# indexer pass-0 histogram: 16-bit counter increment computed with bfe + mad_u24 instead of and/cmp/nop/cndmask (2 fewer VALU per score, 16 per iteration)
# speedup vs baseline: 1.0022x; 1.0022x over previous
; __device__ __forceinline__ unsigned mono_key(float s) { const unsigned u = __float_as_uint(s + 0.0f); return u ^ ((unsigned)((int)u >> 31) | 0x80000000u); }
; __device__ __forceinline__ void idx_scores(const bf16x8 ikf, const bf16x8 (&iq)[2][8], const float (&iw)[2][8], const bf16x8 (&iql)[2][2], float (&sc)[2][4]) {
; #pragma unroll
;     for (int qt = 0; qt < 2; ++qt) {
;         f32x4 L = (f32x4){0.f, 0.f, 0.f, 0.f};
;         L = __builtin_amdgcn_mfma_f32_16x16x32_bf16(ikf, iql[qt][0], L, 0, 0, 0);
;         L = __builtin_amdgcn_mfma_f32_16x16x32_bf16(ikf, iql[qt][1], L, 0, 0, 0);
; #pragma unroll
;         for (int j = 0; j < 4; ++j) sc[qt][j] = L[j];
; #pragma unroll
;         for (int h = 0; h < 8; ++h) {
;             f32x4 a = (f32x4){0.f, 0.f, 0.f, 0.f};
;             a = __builtin_amdgcn_mfma_f32_16x16x32_bf16(ikf, iq[qt][h], a, 0, 0, 0);
; #pragma unroll
;             for (int j = 0; j < 4; ++j) sc[qt][j] = __builtin_fmaf(iw[qt][h], __builtin_fabsf(a[j]), sc[qt][j]);
;         }
;     }
; }
; __device__ __forceinline__ bool indexer_fast(LAS unsigned char* lds, const bf16_t* H, unsigned char* MASKB, int bl, int qb) {
;     ...
;     for (int ks = 0; ks < nks; ++ks) {
;         const int kb = ks * 128 + wid * 16;
;         const bf16x8 ikf = ikn0; ikn0 = ikn1;
;         { const int kn = (ks + 2 < nks) ? ks + 2 : nks - 1; ikn1 = *(const bf16x8*)(ikp + (size_t)kn * 128 * NP1); }
;         float sc[2][4]; idx_scores(ikf, iq, iw, iql, sc);
;         const bool chk = (ks == nks - 1);
; #pragma unroll
;         for (int qt = 0; qt < 2; ++qt) {
;             const int tq = qt ? tq1 : tq0;
; #pragma unroll
;             for (int j = 0; j < 4; ++j) {
;                 const int key = kb + lg * 4 + j;
;                 const unsigned bin = mono_key(sc[qt][j]) >> 21;
;                 unsigned inc = (bin & 1u) ? 65536u : 1u;
;                 if (chk) inc = (key <= tq) ? inc : 0u;
;                 __hip_atomic_fetch_add(&H11[(qt * 16 + lr) * 1025 + (bin >> 1)], inc, __ATOMIC_RELAXED, __HIP_MEMORY_SCOPE_WORKGROUP);
;             }
;         }
;     }
.LBB0_443:
	s_waitcnt vmcnt(0)
	v_mfma_f32_16x16x32_bf16 v[98:101], v[94:97], v[66:69], 0
	v_mfma_f32_16x16x32_bf16 v[102:105], v[94:97], v[74:77], 0
	v_mfma_f32_16x16x32_bf16 v[98:101], v[94:97], v[70:73], v[98:101]
	v_mfma_f32_16x16x32_bf16 v[102:105], v[94:97], v[78:81], v[102:105]
	v_mfma_f32_16x16x32_bf16 v[106:109], v[94:97], v[2:5], 0
	v_mfma_f32_16x16x32_bf16 v[110:113], v[94:97], v[6:9], 0
	v_mfma_f32_16x16x32_bf16 v[114:117], v[94:97], v[10:13], 0
	v_mfma_f32_16x16x32_bf16 v[118:121], v[94:97], v[14:17], 0
	s_add_i32 s0, s13, 2
	v_mov_b64_e32 v[82:83], v[90:91]
	s_min_i32 s0, s0, s96
	v_mov_b64_e32 v[84:85], v[92:93]
	v_mad_i64_i32 v[90:91], s[0:1], s0, v207, v[178:179]
	global_load_dwordx4 v[90:93], v[90:91], off
	v_fma_f32 v98, v163, |v106|, v98
	v_fma_f32 v99, v163, |v107|, v99
	v_fma_f32 v100, v163, |v108|, v100
	v_fma_f32 v101, v163, |v109|, v101
	v_mfma_f32_16x16x32_bf16 v[106:109], v[94:97], v[18:21], 0
	v_fma_f32 v98, v162, |v110|, v98
	v_fma_f32 v99, v162, |v111|, v99
	v_fma_f32 v100, v162, |v112|, v100
	v_fma_f32 v101, v162, |v113|, v101
	v_mfma_f32_16x16x32_bf16 v[110:113], v[94:97], v[22:25], 0
	v_fma_f32 v98, v165, |v114|, v98
	v_fma_f32 v99, v165, |v115|, v99
	v_fma_f32 v100, v165, |v116|, v100
	v_fma_f32 v101, v165, |v117|, v101
	v_mfma_f32_16x16x32_bf16 v[114:117], v[94:97], v[26:29], 0
	v_fma_f32 v98, v164, |v118|, v98
	v_fma_f32 v99, v164, |v119|, v99
	v_fma_f32 v100, v164, |v120|, v100
	v_fma_f32 v101, v164, |v121|, v101
	v_mfma_f32_16x16x32_bf16 v[118:121], v[94:97], v[30:33], 0
	v_fma_f32 v98, v167, |v106|, v98
	v_fma_f32 v99, v167, |v107|, v99
	v_fma_f32 v100, v167, |v108|, v100
	v_fma_f32 v101, v167, |v109|, v101
	v_mfma_f32_16x16x32_bf16 v[106:109], v[94:97], v[62:65], 0
	v_fma_f32 v98, v166, |v110|, v98
	v_fma_f32 v99, v166, |v111|, v99
	v_fma_f32 v100, v166, |v112|, v100
	v_fma_f32 v101, v166, |v113|, v101
	v_mfma_f32_16x16x32_bf16 v[110:113], v[94:97], v[34:37], 0
	v_fma_f32 v98, v169, |v114|, v98
	v_fma_f32 v99, v169, |v115|, v99
	v_fma_f32 v100, v169, |v116|, v100
	v_fma_f32 v101, v169, |v117|, v101
	v_mfma_f32_16x16x32_bf16 v[114:117], v[94:97], v[38:41], 0
	v_fma_f32 v98, v168, |v118|, v98
	v_fma_f32 v99, v168, |v119|, v99
	v_fma_f32 v100, v168, |v120|, v100
	v_fma_f32 v101, v168, |v121|, v101
	v_mfma_f32_16x16x32_bf16 v[118:121], v[94:97], v[42:45], 0
	v_fma_f32 v102, v171, |v106|, v102
	v_fma_f32 v103, v171, |v107|, v103
	v_fma_f32 v104, v171, |v108|, v104
	v_fma_f32 v105, v171, |v109|, v105
	v_mfma_f32_16x16x32_bf16 v[106:109], v[94:97], v[46:49], 0
	v_fma_f32 v102, v170, |v110|, v102
	v_fma_f32 v103, v170, |v111|, v103
	v_fma_f32 v104, v170, |v112|, v104
	v_fma_f32 v105, v170, |v113|, v105
	v_mfma_f32_16x16x32_bf16 v[110:113], v[94:97], v[50:53], 0
	v_fma_f32 v102, v173, |v114|, v102
	v_fma_f32 v103, v173, |v115|, v103
	v_fma_f32 v104, v173, |v116|, v104
	v_fma_f32 v105, v173, |v117|, v105
	v_mfma_f32_16x16x32_bf16 v[114:117], v[94:97], v[54:57], 0
	v_fma_f32 v102, v172, |v118|, v102
	v_fma_f32 v103, v172, |v119|, v103
	v_fma_f32 v104, v172, |v120|, v104
	v_fma_f32 v105, v172, |v121|, v105
	v_mfma_f32_16x16x32_bf16 v[118:121], v[94:97], v[58:61], 0
	v_fma_f32 v102, v175, |v106|, v102
	v_fma_f32 v103, v175, |v107|, v103
	v_fma_f32 v104, v175, |v108|, v104
	v_fma_f32 v105, v175, |v109|, v105
	v_fma_f32 v102, v174, |v110|, v102
	v_fma_f32 v103, v174, |v111|, v103
	v_fma_f32 v104, v174, |v112|, v104
	v_fma_f32 v105, v174, |v113|, v105
	v_fma_f32 v102, v177, |v114|, v102
	v_fma_f32 v103, v177, |v115|, v103
	v_fma_f32 v104, v177, |v116|, v104
	v_fma_f32 v105, v177, |v117|, v105
	v_fma_f32 v102, v176, |v118|, v102
	v_fma_f32 v103, v176, |v119|, v103
	v_fma_f32 v104, v176, |v120|, v104
	v_fma_f32 v105, v176, |v121|, v105
	s_mov_b32 s1, 0xffff
	v_add_f32_e32 v98, 0, v98
	v_ashrrev_i32_e32 v122, 31, v98
	v_or_b32_e32 v122, 0x80000000, v122
	v_xor_b32_e32 v98, v122, v98
	v_bfe_u32 v122, v98, 21, 1
	v_bfe_u32 v123, v98, 22, 10
	v_mad_u32_u24 v122, v122, s1, 1
	v_lshl_add_u32 v123, v123, 2, v0
	ds_add_u32 v123, v122
	v_add_f32_e32 v99, 0, v99
	v_ashrrev_i32_e32 v124, 31, v99
	v_or_b32_e32 v124, 0x80000000, v124
	v_xor_b32_e32 v99, v124, v99
	v_bfe_u32 v124, v99, 21, 1
	v_bfe_u32 v125, v99, 22, 10
	v_mad_u32_u24 v124, v124, s1, 1
	v_lshl_add_u32 v125, v125, 2, v0
	ds_add_u32 v125, v124
	v_add_f32_e32 v100, 0, v100
	v_ashrrev_i32_e32 v180, 31, v100
	v_or_b32_e32 v180, 0x80000000, v180
	v_xor_b32_e32 v100, v180, v100
	v_bfe_u32 v180, v100, 21, 1
	v_bfe_u32 v181, v100, 22, 10
	v_mad_u32_u24 v180, v180, s1, 1
	v_lshl_add_u32 v181, v181, 2, v0
	ds_add_u32 v181, v180
	v_add_f32_e32 v101, 0, v101
	v_ashrrev_i32_e32 v182, 31, v101
	v_or_b32_e32 v182, 0x80000000, v182
	v_xor_b32_e32 v101, v182, v101
	v_bfe_u32 v182, v101, 21, 1
	v_bfe_u32 v183, v101, 22, 10
	v_mad_u32_u24 v182, v182, s1, 1
	v_lshl_add_u32 v183, v183, 2, v0
	ds_add_u32 v183, v182
	v_add_f32_e32 v102, 0, v102
	v_ashrrev_i32_e32 v184, 31, v102
	v_or_b32_e32 v184, 0x80000000, v184
	v_xor_b32_e32 v102, v184, v102
	v_bfe_u32 v184, v102, 21, 1
	v_bfe_u32 v185, v102, 22, 10
	v_mad_u32_u24 v184, v184, s1, 1
	v_lshl_add_u32 v185, v185, 2, v224
	ds_add_u32 v185, v184
	v_add_f32_e32 v103, 0, v103
	v_ashrrev_i32_e32 v186, 31, v103
	v_or_b32_e32 v186, 0x80000000, v186
	v_xor_b32_e32 v103, v186, v103
	v_bfe_u32 v186, v103, 21, 1
	v_bfe_u32 v187, v103, 22, 10
	v_mad_u32_u24 v186, v186, s1, 1
	v_lshl_add_u32 v187, v187, 2, v224
	ds_add_u32 v187, v186
	v_add_f32_e32 v104, 0, v104
	v_ashrrev_i32_e32 v188, 31, v104
	v_or_b32_e32 v188, 0x80000000, v188
	v_xor_b32_e32 v104, v188, v104
	v_bfe_u32 v188, v104, 21, 1
	v_bfe_u32 v189, v104, 22, 10
	v_mad_u32_u24 v188, v188, s1, 1
	v_lshl_add_u32 v189, v189, 2, v224
	ds_add_u32 v189, v188
	v_add_f32_e32 v105, 0, v105
	v_ashrrev_i32_e32 v190, 31, v105
	v_or_b32_e32 v190, 0x80000000, v190
	v_xor_b32_e32 v105, v190, v105
	v_bfe_u32 v190, v105, 21, 1
	v_bfe_u32 v191, v105, 22, 10
	v_mad_u32_u24 v190, v190, s1, 1
	v_lshl_add_u32 v191, v191, 2, v224
	ds_add_u32 v191, v190
	s_add_i32 s13, s13, 1
	s_cmp_eq_u32 s96, s13
	v_mov_b64_e32 v[96:97], v[84:85]
	v_mov_b64_e32 v[94:95], v[82:83]
	s_cbranch_scc0 .LBB0_443
	s_waitcnt vmcnt(0)
	v_add_u32_e32 v90, 0x10040, v223
	s_mov_b64 s[0:1], 0
